# P0 weight-transposition loads: system-scope (sc0 sc1) instead of nt for the read-once f32 weights
# baseline (speedup 1.0000x reference)
.Ltr_dec1:
	s_add_u32 s18, s8, s31
	s_addc_u32 s19, s9, 0
	v_mad_u32_u24 v16, v3, s14, v2
	v_add_u32_e32 v17, s14, v16
	v_add_u32_e32 v18, s14, v17
	v_add_u32_e32 v19, s14, v18
	v_add_u32_e32 v20, s14, v19
	v_add_u32_e32 v21, s14, v20
	v_add_u32_e32 v22, s14, v21
	v_add_u32_e32 v23, s14, v22
	v_mad_u32_u24 v24, v4, s15, v5
	v_add_u32_e32 v25, s15, v24
	v_add_u32_e32 v26, s15, v25
	v_add_u32_e32 v27, s15, v26
	global_load_dwordx4 v[64:67], v16, s[16:17] sc0 sc1
	global_load_dwordx4 v[68:71], v17, s[16:17] sc0 sc1
	global_load_dwordx4 v[72:75], v18, s[16:17] sc0 sc1
	global_load_dwordx4 v[76:79], v19, s[16:17] sc0 sc1
	global_load_dwordx4 v[80:83], v20, s[16:17] sc0 sc1
	global_load_dwordx4 v[84:87], v21, s[16:17] sc0 sc1
	global_load_dwordx4 v[88:91], v22, s[16:17] sc0 sc1
	global_load_dwordx4 v[92:95], v23, s[16:17] sc0 sc1
	global_load_dwordx4 v[96:99], v16, s[16:17] offset:128 sc0 sc1
	global_load_dwordx4 v[100:103], v17, s[16:17] offset:128 sc0 sc1
	global_load_dwordx4 v[104:107], v18, s[16:17] offset:128 sc0 sc1
	global_load_dwordx4 v[108:111], v19, s[16:17] offset:128 sc0 sc1
	global_load_dwordx4 v[112:115], v20, s[16:17] offset:128 sc0 sc1
	global_load_dwordx4 v[116:119], v21, s[16:17] offset:128 sc0 sc1
	global_load_dwordx4 v[120:123], v22, s[16:17] offset:128 sc0 sc1
	global_load_dwordx4 v[124:127], v23, s[16:17] offset:128 sc0 sc1

.Ltr_dec2:
	s_add_u32 s40, s8, s31
	s_addc_u32 s41, s9, 0
	v_mad_u32_u24 v16, v3, s14, v2
	v_add_u32_e32 v17, s14, v16
	v_add_u32_e32 v18, s14, v17
	v_add_u32_e32 v19, s14, v18
	v_add_u32_e32 v20, s14, v19
	v_add_u32_e32 v21, s14, v20
	v_add_u32_e32 v22, s14, v21
	v_add_u32_e32 v23, s14, v22
	v_mad_u32_u24 v28, v4, s15, v5
	v_add_u32_e32 v29, s15, v28
	v_add_u32_e32 v30, s15, v29
	v_add_u32_e32 v31, s15, v30
	global_load_dwordx4 v[128:131], v16, s[16:17] sc0 sc1
	global_load_dwordx4 v[132:135], v17, s[16:17] sc0 sc1
	global_load_dwordx4 v[136:139], v18, s[16:17] sc0 sc1
	global_load_dwordx4 v[140:143], v19, s[16:17] sc0 sc1
	global_load_dwordx4 v[144:147], v20, s[16:17] sc0 sc1
	global_load_dwordx4 v[148:151], v21, s[16:17] sc0 sc1
	global_load_dwordx4 v[152:155], v22, s[16:17] sc0 sc1
	global_load_dwordx4 v[156:159], v23, s[16:17] sc0 sc1
	global_load_dwordx4 v[160:163], v16, s[16:17] offset:128 sc0 sc1
	global_load_dwordx4 v[164:167], v17, s[16:17] offset:128 sc0 sc1
	global_load_dwordx4 v[168:171], v18, s[16:17] offset:128 sc0 sc1
	global_load_dwordx4 v[172:175], v19, s[16:17] offset:128 sc0 sc1
	global_load_dwordx4 v[176:179], v20, s[16:17] offset:128 sc0 sc1
	global_load_dwordx4 v[180:183], v21, s[16:17] offset:128 sc0 sc1
	global_load_dwordx4 v[184:187], v22, s[16:17] offset:128 sc0 sc1
	global_load_dwordx4 v[188:191], v23, s[16:17] offset:128 sc0 sc1
	s_waitcnt vmcnt(16)
	v_cvt_pk_bf16_f32 v192, v64, v68
	v_cvt_pk_bf16_f32 v193, v72, v76
	v_cvt_pk_bf16_f32 v194, v80, v84
	v_cvt_pk_bf16_f32 v195, v88, v92
	v_cvt_pk_bf16_f32 v196, v65, v69
	v_cvt_pk_bf16_f32 v197, v73, v77
	v_cvt_pk_bf16_f32 v198, v81, v85
	v_cvt_pk_bf16_f32 v199, v89, v93
	v_cvt_pk_bf16_f32 v200, v66, v70
	v_cvt_pk_bf16_f32 v201, v74, v78
	v_cvt_pk_bf16_f32 v202, v82, v86
	v_cvt_pk_bf16_f32 v203, v90, v94
	v_cvt_pk_bf16_f32 v204, v67, v71
	v_cvt_pk_bf16_f32 v205, v75, v79
	v_cvt_pk_bf16_f32 v206, v83, v87
	v_cvt_pk_bf16_f32 v207, v91, v95
	global_store_dwordx4 v24, v[192:195], s[18:19] nt
	global_store_dwordx4 v25, v[196:199], s[18:19] nt
	global_store_dwordx4 v26, v[200:203], s[18:19] nt
	global_store_dwordx4 v27, v[204:207], s[18:19] nt
	v_cvt_pk_bf16_f32 v48, v96, v100
	v_cvt_pk_bf16_f32 v49, v104, v108
	v_cvt_pk_bf16_f32 v50, v112, v116
	v_cvt_pk_bf16_f32 v51, v120, v124
	v_cvt_pk_bf16_f32 v52, v97, v101
	v_cvt_pk_bf16_f32 v53, v105, v109
	v_cvt_pk_bf16_f32 v54, v113, v117
	v_cvt_pk_bf16_f32 v55, v121, v125
	v_cvt_pk_bf16_f32 v56, v98, v102
	v_cvt_pk_bf16_f32 v57, v106, v110
	v_cvt_pk_bf16_f32 v58, v114, v118
	v_cvt_pk_bf16_f32 v59, v122, v126
	v_cvt_pk_bf16_f32 v60, v99, v103
	v_cvt_pk_bf16_f32 v61, v107, v111
	v_cvt_pk_bf16_f32 v62, v115, v119
	v_cvt_pk_bf16_f32 v63, v123, v127
	s_add_u32 s10, s18, s34
	s_addc_u32 s11, s19, 0
	global_store_dwordx4 v24, v[48:51], s[10:11] nt
	global_store_dwordx4 v25, v[52:55], s[10:11] nt
	global_store_dwordx4 v26, v[56:59], s[10:11] nt
	global_store_dwordx4 v27, v[60:63], s[10:11] nt
	s_add_u32 s29, s29, s30
	s_cmp_gt_u32 s29, 0xd7ff
	s_cbranch_scc1 .Ltr_lastB
	s_mov_b32 s11, s29
	s_cmp_ge_u32 s11, 0x6c00
	s_cselect_b32 s16, 0x6c00, 0
	s_cselect_b32 s10, 2, 0
	s_sub_u32 s11, s11, s16
	s_cmp_ge_u32 s11, 0x3600
	s_cselect_b32 s16, 0x3600, 0
	s_cselect_b32 s17, 1, 0
	s_sub_u32 s11, s11, s16
	s_add_u32 s10, s10, s17
	s_cmp_lt_u32 s11, 0x2400
	s_cbranch_scc1 .Ltr_in3
	s_cmp_lt_u32 s11, 0x3400
	s_cbranch_scc1 .Ltr_out3
	s_sub_u32 s11, s11, 0x3400
	s_and_b32 s16, s11, 15
	s_lshr_b32 s17, s11, 4
	s_movk_i32 s14, 0x2000
	s_movk_i32 s15, 0x800
	s_mov_b32 s34, 0x10000
	s_lshl_b32 s31, s10, 23
	s_lshl_b32 s11, s16, 19
	s_add_u32 s31, s31, s11
	s_lshl_b32 s11, s17, 8
	s_add_u32 s31, s31, s11
	s_add_u32 s31, s6, s31
	s_addc_u32 s11, s7, 0
	s_bfe_u32 s14, s17, 0x30001
	s_lshl_b32 s14, s14, 8
	s_lshr_b32 s15, s17, 4
	s_lshl_b32 s15, s15, 7
	s_add_u32 s14, s14, s15
	s_and_b32 s15, s17, 1
	s_lshl_b32 s15, s15, 6
	s_add_u32 s14, s14, s15
	s_lshl_b32 s14, s14, 11
	s_lshl_b32 s15, s16, 7
	s_add_u32 s14, s14, s15
	s_lshl_b32 s15, s10, 22
	s_add_u32 s14, s14, s15
	s_add_u32 s17, s14, 0xae00000
	s_mov_b32 s16, s31
	s_mov_b32 s31, s17
	s_mov_b32 s17, s11
	s_movk_i32 s14, 0x2000
	s_movk_i32 s15, 0x800
	s_branch .Ltr_dec3

.Ltr_dec3:
	s_add_u32 s18, s8, s31
	s_addc_u32 s19, s9, 0
	v_mad_u32_u24 v16, v3, s14, v2
	v_add_u32_e32 v17, s14, v16
	v_add_u32_e32 v18, s14, v17
	v_add_u32_e32 v19, s14, v18
	v_add_u32_e32 v20, s14, v19
	v_add_u32_e32 v21, s14, v20
	v_add_u32_e32 v22, s14, v21
	v_add_u32_e32 v23, s14, v22
	v_mad_u32_u24 v24, v4, s15, v5
	v_add_u32_e32 v25, s15, v24
	v_add_u32_e32 v26, s15, v25
	v_add_u32_e32 v27, s15, v26
	global_load_dwordx4 v[64:67], v16, s[16:17] sc0 sc1
	global_load_dwordx4 v[68:71], v17, s[16:17] sc0 sc1
	global_load_dwordx4 v[72:75], v18, s[16:17] sc0 sc1
	global_load_dwordx4 v[76:79], v19, s[16:17] sc0 sc1
	global_load_dwordx4 v[80:83], v20, s[16:17] sc0 sc1
	global_load_dwordx4 v[84:87], v21, s[16:17] sc0 sc1
	global_load_dwordx4 v[88:91], v22, s[16:17] sc0 sc1
	global_load_dwordx4 v[92:95], v23, s[16:17] sc0 sc1
	global_load_dwordx4 v[96:99], v16, s[16:17] offset:128 sc0 sc1
	global_load_dwordx4 v[100:103], v17, s[16:17] offset:128 sc0 sc1
	global_load_dwordx4 v[104:107], v18, s[16:17] offset:128 sc0 sc1
	global_load_dwordx4 v[108:111], v19, s[16:17] offset:128 sc0 sc1
	global_load_dwordx4 v[112:115], v20, s[16:17] offset:128 sc0 sc1
	global_load_dwordx4 v[116:119], v21, s[16:17] offset:128 sc0 sc1
	global_load_dwordx4 v[120:123], v22, s[16:17] offset:128 sc0 sc1
	global_load_dwordx4 v[124:127], v23, s[16:17] offset:128 sc0 sc1
	s_waitcnt vmcnt(16)
	v_cvt_pk_bf16_f32 v192, v128, v132
	v_cvt_pk_bf16_f32 v193, v136, v140
	v_cvt_pk_bf16_f32 v194, v144, v148
	v_cvt_pk_bf16_f32 v195, v152, v156
	v_cvt_pk_bf16_f32 v196, v129, v133
	v_cvt_pk_bf16_f32 v197, v137, v141
	v_cvt_pk_bf16_f32 v198, v145, v149
	v_cvt_pk_bf16_f32 v199, v153, v157
	v_cvt_pk_bf16_f32 v200, v130, v134
	v_cvt_pk_bf16_f32 v201, v138, v142
	v_cvt_pk_bf16_f32 v202, v146, v150
	v_cvt_pk_bf16_f32 v203, v154, v158
	v_cvt_pk_bf16_f32 v204, v131, v135
	v_cvt_pk_bf16_f32 v205, v139, v143
	v_cvt_pk_bf16_f32 v206, v147, v151
	v_cvt_pk_bf16_f32 v207, v155, v159
	global_store_dwordx4 v28, v[192:195], s[40:41] nt
	global_store_dwordx4 v29, v[196:199], s[40:41] nt
	global_store_dwordx4 v30, v[200:203], s[40:41] nt
	global_store_dwordx4 v31, v[204:207], s[40:41] nt
	v_cvt_pk_bf16_f32 v48, v160, v164
	v_cvt_pk_bf16_f32 v49, v168, v172
	v_cvt_pk_bf16_f32 v50, v176, v180
	v_cvt_pk_bf16_f32 v51, v184, v188
	v_cvt_pk_bf16_f32 v52, v161, v165
	v_cvt_pk_bf16_f32 v53, v169, v173
	v_cvt_pk_bf16_f32 v54, v177, v181
	v_cvt_pk_bf16_f32 v55, v185, v189
	v_cvt_pk_bf16_f32 v56, v162, v166
	v_cvt_pk_bf16_f32 v57, v170, v174
	v_cvt_pk_bf16_f32 v58, v178, v182
	v_cvt_pk_bf16_f32 v59, v186, v190
	v_cvt_pk_bf16_f32 v60, v163, v167
	v_cvt_pk_bf16_f32 v61, v171, v175
	v_cvt_pk_bf16_f32 v62, v179, v183
	v_cvt_pk_bf16_f32 v63, v187, v191
	s_add_u32 s10, s40, s35
	s_addc_u32 s11, s41, 0
	global_store_dwordx4 v28, v[48:51], s[10:11] nt
	global_store_dwordx4 v29, v[52:55], s[10:11] nt
	global_store_dwordx4 v30, v[56:59], s[10:11] nt
	global_store_dwordx4 v31, v[60:63], s[10:11] nt
	s_branch .Ltr_loop
